# second-round W_in transposition items moved to the waves of XCDs 4-7 (the half with slack at the P2|P3 barrier)
# speedup vs baseline: 1.0021x; 1.0021x over previous
; __host__ __device__ __forceinline__ int tile_slot(int pn) { if (pn >= 16) return pn - 12; const int q = pn & 7; if (q >= 6) return (pn >> 3) * 2 + (q - 6); return (pn >> 3) * 6 + q; }
; #define LAS __attribute__((address_space(3)))
; __global__ void __launch_bounds__(NWAVES * 64, 2) fwd(Args args) {
;     ...
;         const int gw = vcu * NWAVES + wave, NGW = G * NWAVES;
;         LAS float* scr = (LAS float*)(lds + RING_OFF + wave * 8704);
;         constexpr int I_IN = 16 * 192;
;         for (int it = gw; it < I_IN; it += NGW) { const int kb = it / 192, nb = it % 192, pn = nb >> 3, row = tile_slot(pn) * 256 + (nb & 7) * 32;
;             p0_transpose_item(w_in, PROJW, orig_col(32 * nb), 64 * kb, tile_is_late(pn) ? WING_T : WIN_T, 1024, row, 0, scr, lane); }
.LBB0_17:
	s_or_b64 exec, exec, s[6:7]
	s_add_u32 s84, s60, 0x600000
	s_addc_u32 s5, s61, 0
	s_add_u32 s64, s60, 0xc00000
	s_addc_u32 s65, s61, 0
	s_lshr_b32 s48, s66, 6
	s_load_dwordx16 s[16:31], s[0:1], 0x0
	s_cmp_lt_i32 s56, 1
	s_cselect_b64 s[6:7], -1, 0
	s_cmp_gt_i32 s57, 0
	s_cselect_b64 s[10:11], -1, 0
	s_and_b64 s[6:7], s[6:7], s[10:11]
	s_andn2_b64 vcc, exec, s[6:7]
	v_and_b32_e32 v234, 63, v0
	v_writelane_b32 v240, s48, 2
	s_cbranch_vccnz .LBB0_123
	s_lshl_b32 s3, s8, 3
	s_add_i32 s40, s3, s48
	s_movk_i32 s42, 0x400
	v_lshrrev_b32_e32 v8, 3, v234
	s_cmpk_gt_i32 s40, 0xbff
	v_lshlrev_b32_e32 v9, 3, v0
	v_mov_b32_e32 v3, 0
	v_lshlrev_b32_e32 v34, 2, v8
	s_cbranch_scc1 .LBB0_43
	s_mul_i32 s3, s48, 0x2200
	v_lshlrev_b32_e32 v1, 4, v0
	s_add_i32 s3, s3, 0
	v_and_b32_e32 v2, 0x70, v1
	s_waitcnt lgkmcnt(0)
	v_lshl_add_u64 v[4:5], s[20:21], 0, v[2:3]
	v_add_u32_e32 v15, s3, v2
	v_mul_u32_u24_e32 v16, 0x84, v8
	v_and_b32_e32 v2, 56, v9
	v_mul_u32_u24_e32 v14, 0x84, v2
	v_add_u32_e32 v15, v15, v16
	v_or_b32_e32 v1, 8, v8
	v_or_b32_e32 v6, 16, v8
	v_or_b32_e32 v7, 24, v8
	v_or_b32_e32 v10, 32, v8
	v_or_b32_e32 v11, 40, v8
	v_or_b32_e32 v12, 48, v8
	v_or_b32_e32 v13, 56, v8
	v_add3_u32 v14, s3, v14, v34
	s_lshl_b32 s3, s40, 5
	s_lshl_b32 s4, s42, 5
	s_lshl_b32 s12, s40, 8
	s_lshl_b32 s13, s42, 8
	s_movk_i32 s14, 0x6020
	v_add_u32_e32 v16, 0x420, v15
	v_add_u32_e32 v17, 0x428, v15
	v_add_u32_e32 v18, 0x840, v15
	v_add_u32_e32 v19, 0x848, v15
	v_add_u32_e32 v20, 0xc60, v15
	v_add_u32_e32 v21, 0xc68, v15
	v_add_u32_e32 v22, 0x1080, v15
	v_add_u32_e32 v23, 0x1088, v15
	v_add_u32_e32 v24, 0x14a0, v15
	v_add_u32_e32 v25, 0x14a8, v15
	v_add_u32_e32 v26, 0x18c0, v15
	v_add_u32_e32 v27, 0x18c8, v15
	v_add_u32_e32 v28, 0x1ce0, v15
	v_add_u32_e32 v29, 0x1ce8, v15
	v_lshlrev_b32_e32 v2, 1, v2
	s_mov_b32 s15, s40
	s_branch .LBB0_21
